# v13 + FFN-in fast path double-buffers the C staging (next quadrant written under current compute, one barrier per quadrant)
# speedup vs baseline: 1.0037x; 1.0037x over previous
; DI void stf8(float* p, const F8& f) { *(float4*)p = make_float4(f.v[0], f.v[1], f.v[2], f.v[3]); *(float4*)(p + 4) = make_float4(f.v[4], f.v[5], f.v[6], f.v[7]); }
; DI void stb8(bf16_t* p, const F8& f) { *(uint4*)p = pack8(f); }
; DI float siluf(float x) { return x / (1.f + __expf(-x)); }
; template <int MODE>
; DI void gemm_epilogue(const float* Cs, int m0, int n0, const Epi& ep) {
;     ...
;         const int mt = m0 >> 7, ch0 = (n0 >> 7) * 64, c8 = (tid & 7) * 8, ch = ch0 + c8;
;         const float* cw = ep.c0;
;         const F8 w0 = ldf8(cw + ch), w1 = ldf8(cw + 2816 + ch), w2 = ldf8(cw + 2 * 2816 + ch);
;         const bool defer01 = (m0 < MP) && ((m0 & 8191) != 0);
; #pragma unroll
;         for (int it = 0; it < 2; ++it) {
;             const int i = (tid >> 3) + 64 * it, r = m0 + i;
;             int sq, pos, len; rowinfo(r, sq, pos, len);
;             const F8 g0 = ldf8(Cs + i * LDC + c8), up = ldf8(Cs + i * LDC + 64 + c8);
;             if (i >= 126) stf8(ep.f0 + ((size_t)mt * 2 + (i - 126)) * 2816 + ch, g0);
;             if (i < 2) { stf8(ep.f1 + ((size_t)mt * 2 + i) * 2816 + ch, g0); stf8(ep.f2 + ((size_t)mt * 2 + i) * 2816 + ch, up); }
;             if (pos >= len - 2) {
;                 float* so = sq < 4 ? ep.out + O_PFF + (((size_t)ep.layer * 4 + sq) * 2 + (pos - (len - 2))) * 2816
;                                    : ep.out + O_SFF + (((size_t)ep.layer * 8 + (sq - 4)) * 2 + (pos - (len - 2))) * 2816;
;                 stf8(so + ch, g0);
;             }
;             if (i < 2 && defer01) continue;
;             F8 g1, g2;
;             const float* hist = sq >= 4 ? ep.c1 + ((size_t)ep.layer * 8 + (sq - 4)) * 2 * 2816 + ch : nullptr;
;             if (pos >= 1) g1 = ldf8(Cs + (i - 1) * LDC + c8);
;             else if (hist) g1 = ldf8(hist + 2816);
;             else { for (int e = 0; e < 8; ++e) g1.v[e] = 0.f; }
;             if (pos >= 2) g2 = ldf8(Cs + (i - 2) * LDC + c8);
;             else if (hist) g2 = ldf8(hist + (size_t)pos * 2816);
;             else { for (int e = 0; e < 8; ++e) g2.v[e] = 0.f; }
;             F8 o;
; #pragma unroll
;             for (int e = 0; e < 8; ++e) o.v[e] = siluf(w0.v[e] * g2.v[e] + w1.v[e] * g1.v[e] + w2.v[e] * g0.v[e]) * up.v[e];
;             stb8(ep.b0 + (size_t)r * 2816 + ch, o);
.Lffn_fast:
	s_lshl_b32 s54, s27, 8
	s_lshl_b32 s30, s26, 7
	s_lshl_b32 s31, s27, 2
	v_lshrrev_b32_e32 v195, 3, v250
	v_and_b32_e32 v212, 7, v250
	v_lshlrev_b32_e32 v212, 3, v212
	v_add_u32_e32 v64, s30, v212
	v_add_u32_e32 v65, s54, v195
	s_movk_i32 s0, 0x1600
	v_add_u32_e32 v66, s31, v195
	v_mul_lo_u32 v65, v65, s0
	v_mul_lo_u32 v66, v66, s3
	v_mul_u32_u24_e32 v197, 0x210, v195
	v_lshl_add_u32 v65, v64, 1, v65
	v_lshlrev_b32_e32 v64, 2, v64
	v_lshl_add_u32 v67, v212, 2, 16
	v_add_u32_e32 v66, v66, v64
	v_add_u32_e32 v197, v197, v67
	v_cmp_lt_u32_e64 s[40:41], 1, v195
	v_cmp_gt_u32_e64 s[42:43], 2, v195
	v_cmp_lt_u32_e64 s[44:45], 61, v195
	v_add_u32_e32 v196, 0xfffffbe0, v197
	v_max_i32_e32 v196, v196, v67
	v_add_u32_e32 v156, 0x10800, v194
	v_add_u32_e32 v157, 0x10800, v196
	v_add_u32_e32 v158, 0x10800, v197
	s_mov_b32 s30, 0xbfb8aa3b
	s_mov_b32 s31, 0xbfb8aa3b
	global_load_dwordx4 v[128:131], v64, s[6:7] offset:0
	global_load_dwordx4 v[132:135], v64, s[6:7] offset:16
	global_load_dwordx4 v[136:139], v64, s[14:15] offset:0
	global_load_dwordx4 v[140:143], v64, s[14:15] offset:16
	global_load_dwordx4 v[144:147], v64, s[18:19] offset:0
	global_load_dwordx4 v[148:151], v64, s[18:19] offset:16
	ds_write_b128 v194, v[96:99]
	ds_write_b128 v194, v[100:103] offset:64
	ds_write_b128 v194, v[104:107] offset:8448
	ds_write_b128 v194, v[108:111] offset:8512
	ds_write_b128 v194, v[112:115] offset:16896
	ds_write_b128 v194, v[116:119] offset:16960
	ds_write_b128 v194, v[120:123] offset:25344
	ds_write_b128 v194, v[124:127] offset:25408
	s_waitcnt lgkmcnt(0)
	s_barrier
	ds_read_b128 v[96:99], v197
	ds_read_b128 v[100:103], v197 offset:16
	ds_read_b128 v[104:107], v197 offset:256
	ds_read_b128 v[108:111], v197 offset:272
	ds_read_b128 v[112:115], v196 offset:528
	ds_read_b128 v[116:119], v196 offset:544
	ds_read_b128 v[120:123], v196
	ds_read_b128 v[124:127], v196 offset:16
	s_waitcnt vmcnt(0)
	s_mov_b64 exec, s[42:43]
	s_cbranch_execz .Lffn_f1
	s_waitcnt lgkmcnt(4)
	global_store_dwordx4 v66, v[96:99], s[80:81] offset:0
	global_store_dwordx4 v66, v[100:103], s[80:81] offset:16
	global_store_dwordx4 v66, v[104:107], s[82:83] offset:0
	global_store_dwordx4 v66, v[108:111], s[82:83] offset:16

; DI void stf8(float* p, const F8& f) { *(float4*)p = make_float4(f.v[0], f.v[1], f.v[2], f.v[3]); *(float4*)(p + 4) = make_float4(f.v[4], f.v[5], f.v[6], f.v[7]); }
; DI void stb8(bf16_t* p, const F8& f) { *(uint4*)p = pack8(f); }
; DI float siluf(float x) { return x / (1.f + __expf(-x)); }
; template <int MODE>
; DI void gemm_epilogue(const float* Cs, int m0, int n0, const Epi& ep) {
;     ...
;         const int mt = m0 >> 7, ch0 = (n0 >> 7) * 64, c8 = (tid & 7) * 8, ch = ch0 + c8;
;         const float* cw = ep.c0;
;         const F8 w0 = ldf8(cw + ch), w1 = ldf8(cw + 2816 + ch), w2 = ldf8(cw + 2 * 2816 + ch);
;         const bool defer01 = (m0 < MP) && ((m0 & 8191) != 0);
; #pragma unroll
;         for (int it = 0; it < 2; ++it) {
;             const int i = (tid >> 3) + 64 * it, r = m0 + i;
;             int sq, pos, len; rowinfo(r, sq, pos, len);
;             const F8 g0 = ldf8(Cs + i * LDC + c8), up = ldf8(Cs + i * LDC + 64 + c8);
;             if (i >= 126) stf8(ep.f0 + ((size_t)mt * 2 + (i - 126)) * 2816 + ch, g0);
;             if (i < 2) { stf8(ep.f1 + ((size_t)mt * 2 + i) * 2816 + ch, g0); stf8(ep.f2 + ((size_t)mt * 2 + i) * 2816 + ch, up); }
;             if (pos >= len - 2) {
;                 float* so = sq < 4 ? ep.out + O_PFF + (((size_t)ep.layer * 4 + sq) * 2 + (pos - (len - 2))) * 2816
;                                    : ep.out + O_SFF + (((size_t)ep.layer * 8 + (sq - 4)) * 2 + (pos - (len - 2))) * 2816;
;                 stf8(so + ch, g0);
;             }
;             if (i < 2 && defer01) continue;
;             F8 g1, g2;
;             const float* hist = sq >= 4 ? ep.c1 + ((size_t)ep.layer * 8 + (sq - 4)) * 2 * 2816 + ch : nullptr;
;             if (pos >= 1) g1 = ldf8(Cs + (i - 1) * LDC + c8);
;             else if (hist) g1 = ldf8(hist + 2816);
;             else { for (int e = 0; e < 8; ++e) g1.v[e] = 0.f; }
;             if (pos >= 2) g2 = ldf8(Cs + (i - 2) * LDC + c8);
;             else if (hist) g2 = ldf8(hist + (size_t)pos * 2816);
;             else { for (int e = 0; e < 8; ++e) g2.v[e] = 0.f; }
;             F8 o;
; #pragma unroll
;             for (int e = 0; e < 8; ++e) o.v[e] = siluf(w0.v[e] * g2.v[e] + w1.v[e] * g1.v[e] + w2.v[e] * g0.v[e]) * up.v[e];
;             stb8(ep.b0 + (size_t)r * 2816 + ch, o);
.Lffn_f2:
	s_mov_b64 exec, -1
	s_waitcnt lgkmcnt(0)
	ds_write_b128 v156, v[222:225]
	ds_write_b128 v156, v[68:71] offset:64
	ds_write_b128 v156, v[72:75] offset:8448
	ds_write_b128 v156, v[76:79] offset:8512
	ds_write_b128 v156, v[80:83] offset:16896
	ds_write_b128 v156, v[84:87] offset:16960
	ds_write_b128 v156, v[88:91] offset:25344
	ds_write_b128 v156, v[92:95] offset:25408
	v_pk_mul_f32 v[120:121], v[128:129], v[120:121]
	v_pk_mul_f32 v[122:123], v[130:131], v[122:123]
	v_pk_mul_f32 v[124:125], v[132:133], v[124:125]
	v_pk_mul_f32 v[126:127], v[134:135], v[126:127]
	v_pk_fma_f32 v[120:121], v[136:137], v[112:113], v[120:121]
	v_pk_fma_f32 v[122:123], v[138:139], v[114:115], v[122:123]
	v_pk_fma_f32 v[124:125], v[140:141], v[116:117], v[124:125]
	v_pk_fma_f32 v[126:127], v[142:143], v[118:119], v[126:127]
	v_pk_fma_f32 v[120:121], v[144:145], v[96:97], v[120:121]
	v_pk_fma_f32 v[122:123], v[146:147], v[98:99], v[122:123]
	v_pk_fma_f32 v[124:125], v[148:149], v[100:101], v[124:125]
	v_pk_fma_f32 v[126:127], v[150:151], v[102:103], v[126:127]
	v_pk_mul_f32 v[152:153], v[120:121], s[30:31]
	v_pk_mul_f32 v[154:155], v[122:123], s[30:31]
	v_pk_mul_f32 v[164:165], v[124:125], s[30:31]
	v_pk_mul_f32 v[166:167], v[126:127], s[30:31]
	v_pk_mul_f32 v[120:121], v[104:105], v[120:121]
	v_pk_mul_f32 v[122:123], v[106:107], v[122:123]
	v_pk_mul_f32 v[124:125], v[108:109], v[124:125]
	v_pk_mul_f32 v[126:127], v[110:111], v[126:127]
	v_exp_f32_e32 v152, v152
	v_exp_f32_e32 v153, v153
	v_exp_f32_e32 v154, v154
	v_exp_f32_e32 v155, v155
	v_exp_f32_e32 v164, v164
	v_exp_f32_e32 v165, v165
	v_exp_f32_e32 v166, v166
	v_exp_f32_e32 v167, v167
	v_pk_add_f32 v[152:153], v[152:153], 1.0 op_sel_hi:[1,0]
	v_pk_add_f32 v[154:155], v[154:155], 1.0 op_sel_hi:[1,0]
	v_pk_add_f32 v[164:165], v[164:165], 1.0 op_sel_hi:[1,0]
	v_pk_add_f32 v[166:167], v[166:167], 1.0 op_sel_hi:[1,0]
	v_rcp_f32_e32 v152, v152
	v_rcp_f32_e32 v153, v153
	v_rcp_f32_e32 v154, v154
	v_rcp_f32_e32 v155, v155
	v_rcp_f32_e32 v164, v164
	v_rcp_f32_e32 v165, v165
	v_rcp_f32_e32 v166, v166
	v_rcp_f32_e32 v167, v167
	v_pk_mul_f32 v[120:121], v[120:121], v[152:153]
	v_pk_mul_f32 v[122:123], v[122:123], v[154:155]
	v_pk_mul_f32 v[124:125], v[124:125], v[164:165]
	v_pk_mul_f32 v[126:127], v[126:127], v[166:167]
	v_cvt_pk_bf16_f32 v152, v120, v121
	v_cvt_pk_bf16_f32 v153, v122, v123
	v_cvt_pk_bf16_f32 v154, v124, v125
	v_cvt_pk_bf16_f32 v155, v126, v127
	global_store_dwordx4 v67, v[152:155], s[84:85] offset:0
	global_load_dwordx4 v[128:131], v64, s[6:7] offset:256
	global_load_dwordx4 v[132:135], v64, s[6:7] offset:272
	global_load_dwordx4 v[136:139], v64, s[14:15] offset:256
	global_load_dwordx4 v[140:143], v64, s[14:15] offset:272
	global_load_dwordx4 v[144:147], v64, s[18:19] offset:256
	global_load_dwordx4 v[148:151], v64, s[18:19] offset:272
	s_waitcnt lgkmcnt(0)
	s_barrier
	ds_read_b128 v[96:99], v158
	ds_read_b128 v[100:103], v158 offset:16
	ds_read_b128 v[104:107], v158 offset:256
	ds_read_b128 v[108:111], v158 offset:272
	ds_read_b128 v[112:115], v157 offset:528
	ds_read_b128 v[116:119], v157 offset:544
	ds_read_b128 v[120:123], v157
	ds_read_b128 v[124:127], v157 offset:16
	s_waitcnt vmcnt(0)
	s_mov_b64 exec, s[42:43]
	s_cbranch_execz .Lffn_f3
	s_waitcnt lgkmcnt(4)
	global_store_dwordx4 v66, v[96:99], s[80:81] offset:256
	global_store_dwordx4 v66, v[100:103], s[80:81] offset:272
	global_store_dwordx4 v66, v[104:107], s[82:83] offset:256
	global_store_dwordx4 v66, v[108:111], s[82:83] offset:272

; DI void stf8(float* p, const F8& f) { *(float4*)p = make_float4(f.v[0], f.v[1], f.v[2], f.v[3]); *(float4*)(p + 4) = make_float4(f.v[4], f.v[5], f.v[6], f.v[7]); }
; DI void stb8(bf16_t* p, const F8& f) { *(uint4*)p = pack8(f); }
; DI float siluf(float x) { return x / (1.f + __expf(-x)); }
; template <int MODE>
; DI void gemm_epilogue(const float* Cs, int m0, int n0, const Epi& ep) {
;     ...
;         const int mt = m0 >> 7, ch0 = (n0 >> 7) * 64, c8 = (tid & 7) * 8, ch = ch0 + c8;
;         const float* cw = ep.c0;
;         const F8 w0 = ldf8(cw + ch), w1 = ldf8(cw + 2816 + ch), w2 = ldf8(cw + 2 * 2816 + ch);
;         const bool defer01 = (m0 < MP) && ((m0 & 8191) != 0);
; #pragma unroll
;         for (int it = 0; it < 2; ++it) {
;             const int i = (tid >> 3) + 64 * it, r = m0 + i;
;             int sq, pos, len; rowinfo(r, sq, pos, len);
;             const F8 g0 = ldf8(Cs + i * LDC + c8), up = ldf8(Cs + i * LDC + 64 + c8);
;             if (i >= 126) stf8(ep.f0 + ((size_t)mt * 2 + (i - 126)) * 2816 + ch, g0);
;             if (i < 2) { stf8(ep.f1 + ((size_t)mt * 2 + i) * 2816 + ch, g0); stf8(ep.f2 + ((size_t)mt * 2 + i) * 2816 + ch, up); }
;             if (pos >= len - 2) {
;                 float* so = sq < 4 ? ep.out + O_PFF + (((size_t)ep.layer * 4 + sq) * 2 + (pos - (len - 2))) * 2816
;                                    : ep.out + O_SFF + (((size_t)ep.layer * 8 + (sq - 4)) * 2 + (pos - (len - 2))) * 2816;
;                 stf8(so + ch, g0);
;             }
;             if (i < 2 && defer01) continue;
;             F8 g1, g2;
;             const float* hist = sq >= 4 ? ep.c1 + ((size_t)ep.layer * 8 + (sq - 4)) * 2 * 2816 + ch : nullptr;
;             if (pos >= 1) g1 = ldf8(Cs + (i - 1) * LDC + c8);
;             else if (hist) g1 = ldf8(hist + 2816);
;             else { for (int e = 0; e < 8; ++e) g1.v[e] = 0.f; }
;             if (pos >= 2) g2 = ldf8(Cs + (i - 2) * LDC + c8);
;             else if (hist) g2 = ldf8(hist + (size_t)pos * 2816);
;             else { for (int e = 0; e < 8; ++e) g2.v[e] = 0.f; }
;             F8 o;
; #pragma unroll
;             for (int e = 0; e < 8; ++e) o.v[e] = siluf(w0.v[e] * g2.v[e] + w1.v[e] * g1.v[e] + w2.v[e] * g0.v[e]) * up.v[e];
;             stb8(ep.b0 + (size_t)r * 2816 + ch, o);
.Lffn_f4:
	s_mov_b64 exec, -1
	s_waitcnt lgkmcnt(0)
	ds_write_b128 v194, v[32:35]
	ds_write_b128 v194, v[36:39] offset:64
	ds_write_b128 v194, v[40:43] offset:8448
	ds_write_b128 v194, v[44:47] offset:8512
	ds_write_b128 v194, v[48:51] offset:16896
	ds_write_b128 v194, v[52:55] offset:16960
	ds_write_b128 v194, v[56:59] offset:25344
	ds_write_b128 v194, v[60:63] offset:25408
	v_pk_mul_f32 v[120:121], v[128:129], v[120:121]
	v_pk_mul_f32 v[122:123], v[130:131], v[122:123]
	v_pk_mul_f32 v[124:125], v[132:133], v[124:125]
	v_pk_mul_f32 v[126:127], v[134:135], v[126:127]
	v_pk_fma_f32 v[120:121], v[136:137], v[112:113], v[120:121]
	v_pk_fma_f32 v[122:123], v[138:139], v[114:115], v[122:123]
	v_pk_fma_f32 v[124:125], v[140:141], v[116:117], v[124:125]
	v_pk_fma_f32 v[126:127], v[142:143], v[118:119], v[126:127]
	v_pk_fma_f32 v[120:121], v[144:145], v[96:97], v[120:121]
	v_pk_fma_f32 v[122:123], v[146:147], v[98:99], v[122:123]
	v_pk_fma_f32 v[124:125], v[148:149], v[100:101], v[124:125]
	v_pk_fma_f32 v[126:127], v[150:151], v[102:103], v[126:127]
	v_pk_mul_f32 v[152:153], v[120:121], s[30:31]
	v_pk_mul_f32 v[154:155], v[122:123], s[30:31]
	v_pk_mul_f32 v[164:165], v[124:125], s[30:31]
	v_pk_mul_f32 v[166:167], v[126:127], s[30:31]
	v_pk_mul_f32 v[120:121], v[104:105], v[120:121]
	v_pk_mul_f32 v[122:123], v[106:107], v[122:123]
	v_pk_mul_f32 v[124:125], v[108:109], v[124:125]
	v_pk_mul_f32 v[126:127], v[110:111], v[126:127]
	v_exp_f32_e32 v152, v152
	v_exp_f32_e32 v153, v153
	v_exp_f32_e32 v154, v154
	v_exp_f32_e32 v155, v155
	v_exp_f32_e32 v164, v164
	v_exp_f32_e32 v165, v165
	v_exp_f32_e32 v166, v166
	v_exp_f32_e32 v167, v167
	v_pk_add_f32 v[152:153], v[152:153], 1.0 op_sel_hi:[1,0]
	v_pk_add_f32 v[154:155], v[154:155], 1.0 op_sel_hi:[1,0]
	v_pk_add_f32 v[164:165], v[164:165], 1.0 op_sel_hi:[1,0]
	v_pk_add_f32 v[166:167], v[166:167], 1.0 op_sel_hi:[1,0]
	v_rcp_f32_e32 v152, v152
	v_rcp_f32_e32 v153, v153
	v_rcp_f32_e32 v154, v154
	v_rcp_f32_e32 v155, v155
	v_rcp_f32_e32 v164, v164
	v_rcp_f32_e32 v165, v165
	v_rcp_f32_e32 v166, v166
	v_rcp_f32_e32 v167, v167
	v_pk_mul_f32 v[120:121], v[120:121], v[152:153]
	v_pk_mul_f32 v[122:123], v[122:123], v[154:155]
	v_pk_mul_f32 v[124:125], v[124:125], v[164:165]
	v_pk_mul_f32 v[126:127], v[126:127], v[166:167]
	v_cvt_pk_bf16_f32 v152, v120, v121
	v_cvt_pk_bf16_f32 v153, v122, v123
	v_cvt_pk_bf16_f32 v154, v124, v125
	v_cvt_pk_bf16_f32 v155, v126, v127
	global_store_dwordx4 v67, v[152:155], s[84:85] offset:128
	global_load_dwordx4 v[128:131], v64, s[6:7] offset:0
	global_load_dwordx4 v[132:135], v64, s[6:7] offset:16
	global_load_dwordx4 v[136:139], v64, s[14:15] offset:0
	global_load_dwordx4 v[140:143], v64, s[14:15] offset:16
	global_load_dwordx4 v[144:147], v64, s[18:19] offset:0
	global_load_dwordx4 v[148:151], v64, s[18:19] offset:16
	s_waitcnt lgkmcnt(0)
	s_barrier
	ds_read_b128 v[96:99], v197
	ds_read_b128 v[100:103], v197 offset:16
	ds_read_b128 v[104:107], v197 offset:256
	ds_read_b128 v[108:111], v197 offset:272
	ds_read_b128 v[112:115], v196 offset:528
	ds_read_b128 v[116:119], v196 offset:544
	ds_read_b128 v[120:123], v196
	ds_read_b128 v[124:127], v196 offset:16
	v_add_u32_e32 v67, 0xb0000, v65
	s_waitcnt vmcnt(0)
	s_mov_b64 exec, s[42:43]
	s_cbranch_execz .Lffn_f5
	v_add_u32_e32 v212, 0x5800, v66
	s_waitcnt lgkmcnt(4)
	global_store_dwordx4 v212, v[96:99], s[80:81] offset:0
	global_store_dwordx4 v212, v[100:103], s[80:81] offset:16
	global_store_dwordx4 v212, v[104:107], s[82:83] offset:0
	global_store_dwordx4 v212, v[108:111], s[82:83] offset:16

; DI void stf8(float* p, const F8& f) { *(float4*)p = make_float4(f.v[0], f.v[1], f.v[2], f.v[3]); *(float4*)(p + 4) = make_float4(f.v[4], f.v[5], f.v[6], f.v[7]); }
; DI void stb8(bf16_t* p, const F8& f) { *(uint4*)p = pack8(f); }
; DI float siluf(float x) { return x / (1.f + __expf(-x)); }
; template <int MODE>
; DI void gemm_epilogue(const float* Cs, int m0, int n0, const Epi& ep) {
;     ...
;         const int mt = m0 >> 7, ch0 = (n0 >> 7) * 64, c8 = (tid & 7) * 8, ch = ch0 + c8;
;         const float* cw = ep.c0;
;         const F8 w0 = ldf8(cw + ch), w1 = ldf8(cw + 2816 + ch), w2 = ldf8(cw + 2 * 2816 + ch);
;         const bool defer01 = (m0 < MP) && ((m0 & 8191) != 0);
; #pragma unroll
;         for (int it = 0; it < 2; ++it) {
;             const int i = (tid >> 3) + 64 * it, r = m0 + i;
;             int sq, pos, len; rowinfo(r, sq, pos, len);
;             const F8 g0 = ldf8(Cs + i * LDC + c8), up = ldf8(Cs + i * LDC + 64 + c8);
;             if (i >= 126) stf8(ep.f0 + ((size_t)mt * 2 + (i - 126)) * 2816 + ch, g0);
;             if (i < 2) { stf8(ep.f1 + ((size_t)mt * 2 + i) * 2816 + ch, g0); stf8(ep.f2 + ((size_t)mt * 2 + i) * 2816 + ch, up); }
;             if (pos >= len - 2) {
;                 float* so = sq < 4 ? ep.out + O_PFF + (((size_t)ep.layer * 4 + sq) * 2 + (pos - (len - 2))) * 2816
;                                    : ep.out + O_SFF + (((size_t)ep.layer * 8 + (sq - 4)) * 2 + (pos - (len - 2))) * 2816;
;                 stf8(so + ch, g0);
;             }
;             if (i < 2 && defer01) continue;
;             F8 g1, g2;
;             const float* hist = sq >= 4 ? ep.c1 + ((size_t)ep.layer * 8 + (sq - 4)) * 2 * 2816 + ch : nullptr;
;             if (pos >= 1) g1 = ldf8(Cs + (i - 1) * LDC + c8);
;             else if (hist) g1 = ldf8(hist + 2816);
;             else { for (int e = 0; e < 8; ++e) g1.v[e] = 0.f; }
;             if (pos >= 2) g2 = ldf8(Cs + (i - 2) * LDC + c8);
;             else if (hist) g2 = ldf8(hist + (size_t)pos * 2816);
;             else { for (int e = 0; e < 8; ++e) g2.v[e] = 0.f; }
;             F8 o;
; #pragma unroll
;             for (int e = 0; e < 8; ++e) o.v[e] = siluf(w0.v[e] * g2.v[e] + w1.v[e] * g1.v[e] + w2.v[e] * g0.v[e]) * up.v[e];
;             stb8(ep.b0 + (size_t)r * 2816 + ch, o);
.Lffn_f6:
	s_mov_b64 exec, -1
	s_waitcnt lgkmcnt(0)
	ds_write_b128 v156, v[0:3]
	ds_write_b128 v156, v[4:7] offset:64
	ds_write_b128 v156, v[8:11] offset:8448
	ds_write_b128 v156, v[12:15] offset:8512
	ds_write_b128 v156, v[16:19] offset:16896
	ds_write_b128 v156, v[20:23] offset:16960
	ds_write_b128 v156, v[24:27] offset:25344
	ds_write_b128 v156, v[28:31] offset:25408
	v_pk_mul_f32 v[120:121], v[128:129], v[120:121]
	v_pk_mul_f32 v[122:123], v[130:131], v[122:123]
	v_pk_mul_f32 v[124:125], v[132:133], v[124:125]
	v_pk_mul_f32 v[126:127], v[134:135], v[126:127]
	v_pk_fma_f32 v[120:121], v[136:137], v[112:113], v[120:121]
	v_pk_fma_f32 v[122:123], v[138:139], v[114:115], v[122:123]
	v_pk_fma_f32 v[124:125], v[140:141], v[116:117], v[124:125]
	v_pk_fma_f32 v[126:127], v[142:143], v[118:119], v[126:127]
	v_pk_fma_f32 v[120:121], v[144:145], v[96:97], v[120:121]
	v_pk_fma_f32 v[122:123], v[146:147], v[98:99], v[122:123]
	v_pk_fma_f32 v[124:125], v[148:149], v[100:101], v[124:125]
	v_pk_fma_f32 v[126:127], v[150:151], v[102:103], v[126:127]
	v_pk_mul_f32 v[152:153], v[120:121], s[30:31]
	v_pk_mul_f32 v[154:155], v[122:123], s[30:31]
	v_pk_mul_f32 v[164:165], v[124:125], s[30:31]
	v_pk_mul_f32 v[166:167], v[126:127], s[30:31]
	v_pk_mul_f32 v[120:121], v[104:105], v[120:121]
	v_pk_mul_f32 v[122:123], v[106:107], v[122:123]
	v_pk_mul_f32 v[124:125], v[108:109], v[124:125]
	v_pk_mul_f32 v[126:127], v[110:111], v[126:127]
	v_exp_f32_e32 v152, v152
	v_exp_f32_e32 v153, v153
	v_exp_f32_e32 v154, v154
	v_exp_f32_e32 v155, v155
	v_exp_f32_e32 v164, v164
	v_exp_f32_e32 v165, v165
	v_exp_f32_e32 v166, v166
	v_exp_f32_e32 v167, v167
	v_pk_add_f32 v[152:153], v[152:153], 1.0 op_sel_hi:[1,0]
	v_pk_add_f32 v[154:155], v[154:155], 1.0 op_sel_hi:[1,0]
	v_pk_add_f32 v[164:165], v[164:165], 1.0 op_sel_hi:[1,0]
	v_pk_add_f32 v[166:167], v[166:167], 1.0 op_sel_hi:[1,0]
	v_rcp_f32_e32 v152, v152
	v_rcp_f32_e32 v153, v153
	v_rcp_f32_e32 v154, v154
	v_rcp_f32_e32 v155, v155
	v_rcp_f32_e32 v164, v164
	v_rcp_f32_e32 v165, v165
	v_rcp_f32_e32 v166, v166
	v_rcp_f32_e32 v167, v167
	v_pk_mul_f32 v[120:121], v[120:121], v[152:153]
	v_pk_mul_f32 v[122:123], v[122:123], v[154:155]
	v_pk_mul_f32 v[124:125], v[124:125], v[164:165]
	v_pk_mul_f32 v[126:127], v[126:127], v[166:167]
	v_cvt_pk_bf16_f32 v152, v120, v121
	v_cvt_pk_bf16_f32 v153, v122, v123
	v_cvt_pk_bf16_f32 v154, v124, v125
	v_cvt_pk_bf16_f32 v155, v126, v127
	global_store_dwordx4 v67, v[152:155], s[84:85] offset:0
	global_load_dwordx4 v[128:131], v64, s[6:7] offset:256
	global_load_dwordx4 v[132:135], v64, s[6:7] offset:272
	global_load_dwordx4 v[136:139], v64, s[14:15] offset:256
	global_load_dwordx4 v[140:143], v64, s[14:15] offset:272
	global_load_dwordx4 v[144:147], v64, s[18:19] offset:256
	global_load_dwordx4 v[148:151], v64, s[18:19] offset:272
	s_waitcnt lgkmcnt(0)
	s_barrier
	ds_read_b128 v[96:99], v158
	ds_read_b128 v[100:103], v158 offset:16
	ds_read_b128 v[104:107], v158 offset:256
	ds_read_b128 v[108:111], v158 offset:272
	ds_read_b128 v[112:115], v157 offset:528
	ds_read_b128 v[116:119], v157 offset:544
	ds_read_b128 v[120:123], v157
	ds_read_b128 v[124:127], v157 offset:16
	v_add_u32_e32 v67, 0xb0000, v65
	s_waitcnt vmcnt(0)
	s_mov_b64 exec, s[42:43]
	s_cbranch_execz .Lffn_f7
	v_add_u32_e32 v212, 0x5800, v66
	s_waitcnt lgkmcnt(4)
	global_store_dwordx4 v212, v[96:99], s[80:81] offset:256
	global_store_dwordx4 v212, v[100:103], s[80:81] offset:272
	global_store_dwordx4 v212, v[104:107], s[82:83] offset:256
	global_store_dwordx4 v212, v[108:111], s[82:83] offset:272
